# bundle2 + in-proj epilogue reads the rope table from LDS (staged once) instead of global loads queued behind its stores
# speedup vs baseline: 1.0110x; 1.0110x over previous
.LBB0_131:
	s_or_b64 exec, exec, s[4:5]
	v_mov_b32_e32 v8, v198
	s_waitcnt lgkmcnt(0)
	s_barrier
	v_lshlrev_b32_e32 v249, 4, v198
	s_add_u32 s88, s44, 0x40000
	s_addc_u32 s89, s45, 0
	global_load_dwordx4 v[250:253], v249, s[88:89]
	v_add_u32_e32 v254, 0x20400, v249
	v_lshlrev_b32_e32 v249, 2, v198
	v_and_b32_e32 v249, 64, v249
	v_add_u32_e32 v249, 0x20400, v249
	s_waitcnt vmcnt(0)
	ds_write_b128 v254, v[250:253]
	s_waitcnt lgkmcnt(0)
	s_cmpk_gt_i32 s2, 0xfff
	v_readfirstlane_b32 s14, v8
	s_cbranch_scc0 .LBB0_134
	s_mov_b64 s[6:7], 0
	s_cmpk_gt_u32 s2, 0x10bf
	s_mov_b64 s[4:5], 0
	s_cbranch_scc1 .LBB0_135
	s_add_i32 s3, s2, 0xfffff000
	s_cmpk_lt_u32 s3, 0x80
	s_cselect_b32 s4, 4, 8
	s_lshr_b32 s3, s3, 4
	s_add_i32 s22, s4, s3
	s_and_b32 s3, s2, 15
	s_or_b32 s24, s3, 0x80
	s_mov_b64 s[4:5], -1
	s_branch .LBB0_135

.LBB0_176:
	s_lshr_b32 s15, s15, 6
	s_add_i32 s15, s15, s69
	v_mov_b32_e32 v164, s15
	v_cndmask_b32_e64 v164, v174, v164, s[4:5]
	v_lshlrev_b32_e32 v164, 4, v164
	v_ashrrev_i32_e32 v165, 31, v164
	s_andn2_b64 vcc, exec, s[36:37]
	v_lshl_add_u32 v164, v164, 3, v249
	s_cbranch_vccnz .LBB0_180
	s_cmp_eq_u32 s13, 1
	s_cbranch_scc0 .LBB0_179
	ds_read_b128 v[166:169], v164
	ds_read_b128 v[170:173], v164 offset:16
	ds_read_b128 v[182:185], v164 offset:32
	ds_read_b128 v[186:189], v164 offset:48
	v_and_b32_e32 v192, 64, v181
	v_xor_b32_e32 v191, 32, v181
	v_add_u32_e32 v192, 64, v192
	v_cmp_lt_i32_e32 vcc, v191, v192
	v_mov_b32_e32 v190, v123
	s_waitcnt lgkmcnt(0)
	v_mov_b32_e32 v201, v168
	v_cndmask_b32_e32 v191, v181, v191, vcc
	v_lshlrev_b32_e32 v191, 2, v191
	ds_bpermute_b32 v194, v191, v126
	ds_bpermute_b32 v195, v191, v127
	ds_bpermute_b32 v199, v191, v122
	ds_bpermute_b32 v123, v191, v123
	ds_bpermute_b32 v192, v191, v124
	ds_bpermute_b32 v193, v191, v125
	ds_bpermute_b32 v196, v191, v120
	ds_bpermute_b32 v197, v191, v121
	s_waitcnt lgkmcnt(6)
	v_pk_mul_f32 v[194:195], v[140:141], v[194:195]
	s_waitcnt lgkmcnt(5)
	v_mul_f32_e32 v199, v140, v199
	s_waitcnt lgkmcnt(4)
	v_mul_f32_e32 v191, v140, v123
	v_mov_b32_e32 v168, v167
	v_mov_b32_e32 v167, v172
	v_mov_b32_e32 v172, v171
	s_waitcnt lgkmcnt(2)
	v_pk_mul_f32 v[192:193], v[140:141], v[192:193]
	s_waitcnt lgkmcnt(0)
	v_pk_mul_f32 v[196:197], v[140:141], v[196:197]
	v_mov_b32_e32 v200, v166
	v_mov_b32_e32 v166, v170
	v_pk_mul_f32 v[170:171], v[194:195], v[172:173]
	v_mov_b32_e32 v172, v182
	v_mov_b32_e32 v173, v184
	v_mov_b32_e32 v184, v183
	v_mul_f32_e32 v122, v122, v186
	v_mul_f32_e32 v182, v199, v187
	v_pk_mul_f32 v[186:187], v[190:191], v[188:189]
	v_pk_mul_f32 v[168:169], v[192:193], v[168:169]
	v_pk_mul_f32 v[184:185], v[196:197], v[184:185]
	v_mov_b32_e32 v123, v186
	v_mov_b32_e32 v183, v187
	v_pk_fma_f32 v[124:125], v[124:125], v[200:201], v[168:169]
	v_pk_fma_f32 v[126:127], v[126:127], v[166:167], v[170:171]
	v_pk_fma_f32 v[120:121], v[120:121], v[172:173], v[184:185]
	v_pk_add_f32 v[122:123], v[122:123], v[182:183]
	v_pk_mul_f32 v[168:169], s[22:23], v[126:127] op_sel_hi:[0,1]
	v_pk_mul_f32 v[166:167], s[22:23], v[124:125] op_sel_hi:[0,1]
	v_pk_mul_f32 v[172:173], s[22:23], v[122:123] op_sel_hi:[0,1]
	v_pk_mul_f32 v[170:171], s[22:23], v[120:121] op_sel_hi:[0,1]
	s_branch .LBB0_180

.LBB0_182:
	s_andn2_b64 vcc, exec, s[28:29]
	s_cbranch_vccnz .LBB0_186
	s_cmp_eq_u32 s13, 1
	s_cbranch_scc0 .LBB0_185
	ds_read_b128 v[124:127], v164
	ds_read_b128 v[166:169], v164 offset:16
	ds_read_b128 v[170:173], v164 offset:32
	ds_read_b128 v[182:185], v164 offset:48
	v_and_b32_e32 v186, 64, v181
	v_xor_b32_e32 v165, 32, v181
	v_add_u32_e32 v186, 64, v186
	v_cmp_lt_i32_e32 vcc, v165, v186
	v_mov_b32_e32 v164, v115
	s_waitcnt lgkmcnt(0)
	v_mov_b32_e32 v193, v126
	v_cndmask_b32_e32 v165, v181, v165, vcc
	v_lshlrev_b32_e32 v165, 2, v165
	ds_bpermute_b32 v188, v165, v118
	ds_bpermute_b32 v189, v165, v119
	ds_bpermute_b32 v115, v165, v115
	ds_bpermute_b32 v186, v165, v116
	ds_bpermute_b32 v187, v165, v117
	ds_bpermute_b32 v190, v165, v112
	ds_bpermute_b32 v191, v165, v113
	ds_bpermute_b32 v192, v165, v114
	s_waitcnt lgkmcnt(6)
	v_pk_mul_f32 v[188:189], v[140:141], v[188:189]
	s_waitcnt lgkmcnt(5)
	v_mul_f32_e32 v165, v140, v115
	v_mov_b32_e32 v126, v125
	v_mov_b32_e32 v125, v168
	v_mov_b32_e32 v168, v167
	s_waitcnt lgkmcnt(3)
	v_pk_mul_f32 v[186:187], v[140:141], v[186:187]
	s_waitcnt lgkmcnt(1)
	v_pk_mul_f32 v[190:191], v[140:141], v[190:191]
	s_waitcnt lgkmcnt(0)
	v_mul_f32_e32 v194, v140, v192
	v_mov_b32_e32 v192, v124
	v_mov_b32_e32 v124, v166
	v_pk_mul_f32 v[166:167], v[188:189], v[168:169]
	v_mov_b32_e32 v169, v172
	v_mov_b32_e32 v172, v171
	v_pk_mul_f32 v[164:165], v[164:165], v[184:185]
	v_pk_mul_f32 v[126:127], v[186:187], v[126:127]
	v_mov_b32_e32 v168, v170
	v_mul_f32_e32 v114, v114, v182
	v_mul_f32_e32 v170, v194, v183
	v_pk_mul_f32 v[172:173], v[190:191], v[172:173]
	v_mov_b32_e32 v115, v164
	v_mov_b32_e32 v171, v165
	v_pk_fma_f32 v[116:117], v[116:117], v[192:193], v[126:127]
	v_pk_fma_f32 v[118:119], v[118:119], v[124:125], v[166:167]
	v_pk_fma_f32 v[112:113], v[112:113], v[168:169], v[172:173]
	v_pk_add_f32 v[114:115], v[114:115], v[170:171]
	v_pk_mul_f32 v[126:127], s[22:23], v[118:119] op_sel_hi:[0,1]
	v_pk_mul_f32 v[124:125], s[22:23], v[116:117] op_sel_hi:[0,1]
	v_pk_mul_f32 v[168:169], s[22:23], v[114:115] op_sel_hi:[0,1]
	v_pk_mul_f32 v[166:167], s[22:23], v[112:113] op_sel_hi:[0,1]
	s_branch .LBB0_186

.LBB0_188:
	v_mov_b32_e32 v112, s15
	v_cndmask_b32_e64 v112, v176, v112, s[4:5]
	v_lshlrev_b32_e32 v112, 4, v112
	v_ashrrev_i32_e32 v113, 31, v112
	s_andn2_b64 vcc, exec, s[28:29]
	v_lshl_add_u32 v112, v112, 3, v249
	s_cbranch_vccnz .LBB0_192
	s_cmp_eq_u32 s13, 1
	s_cbranch_scc0 .LBB0_191
	ds_read_b128 v[114:117], v112
	ds_read_b128 v[122:125], v112 offset:16
	ds_read_b128 v[164:167], v112 offset:32
	ds_read_b128 v[168:171], v112 offset:48
	v_and_b32_e32 v126, 64, v181
	v_xor_b32_e32 v119, 32, v181
	v_add_u32_e32 v126, 64, v126
	v_cmp_lt_i32_e32 vcc, v119, v126
	v_mov_b32_e32 v118, v107
	s_waitcnt lgkmcnt(0)
	v_mov_b32_e32 v185, v116
	v_cndmask_b32_e32 v119, v181, v119, vcc
	v_lshlrev_b32_e32 v119, 2, v119
	ds_bpermute_b32 v172, v119, v110
	ds_bpermute_b32 v173, v119, v111
	ds_bpermute_b32 v107, v119, v107
	ds_bpermute_b32 v126, v119, v108
	ds_bpermute_b32 v127, v119, v109
	ds_bpermute_b32 v182, v119, v104
	ds_bpermute_b32 v183, v119, v105
	ds_bpermute_b32 v184, v119, v106
	s_waitcnt lgkmcnt(6)
	v_pk_mul_f32 v[172:173], v[140:141], v[172:173]
	s_waitcnt lgkmcnt(5)
	v_mul_f32_e32 v119, v140, v107
	v_mov_b32_e32 v116, v115
	v_mov_b32_e32 v115, v124
	v_mov_b32_e32 v124, v123
	s_waitcnt lgkmcnt(3)
	v_pk_mul_f32 v[126:127], v[140:141], v[126:127]
	s_waitcnt lgkmcnt(1)
	v_pk_mul_f32 v[182:183], v[140:141], v[182:183]
	s_waitcnt lgkmcnt(0)
	v_mul_f32_e32 v186, v140, v184
	v_mov_b32_e32 v184, v114
	v_mov_b32_e32 v114, v122
	v_pk_mul_f32 v[122:123], v[172:173], v[124:125]
	v_mov_b32_e32 v125, v166
	v_mov_b32_e32 v166, v165
	v_pk_mul_f32 v[118:119], v[118:119], v[170:171]
	v_pk_mul_f32 v[116:117], v[126:127], v[116:117]
	v_mov_b32_e32 v124, v164
	v_mul_f32_e32 v106, v106, v168
	v_mul_f32_e32 v126, v186, v169
	v_pk_mul_f32 v[164:165], v[182:183], v[166:167]
	v_mov_b32_e32 v107, v118
	v_mov_b32_e32 v127, v119
	v_pk_fma_f32 v[108:109], v[108:109], v[184:185], v[116:117]
	v_pk_fma_f32 v[110:111], v[110:111], v[114:115], v[122:123]
	v_pk_fma_f32 v[104:105], v[104:105], v[124:125], v[164:165]
	v_pk_add_f32 v[106:107], v[106:107], v[126:127]
	v_pk_mul_f32 v[116:117], s[22:23], v[110:111] op_sel_hi:[0,1]
	v_pk_mul_f32 v[114:115], s[22:23], v[108:109] op_sel_hi:[0,1]
	v_pk_mul_f32 v[122:123], s[22:23], v[106:107] op_sel_hi:[0,1]
	v_pk_mul_f32 v[118:119], s[22:23], v[104:105] op_sel_hi:[0,1]
	s_branch .LBB0_192

.LBB0_194:
	s_andn2_b64 vcc, exec, s[28:29]
	s_cbranch_vccnz .LBB0_198
	s_cmp_eq_u32 s13, 1
	s_cbranch_scc0 .LBB0_197
	ds_read_b128 v[106:109], v112
	ds_read_b128 v[114:117], v112 offset:16
	ds_read_b128 v[122:125], v112 offset:32
	s_nop 0
	ds_read_b128 v[110:113], v112 offset:48
	v_and_b32_e32 v126, 64, v181
	v_xor_b32_e32 v119, 32, v181
	v_add_u32_e32 v126, 64, v126
	v_cmp_lt_i32_e32 vcc, v119, v126
	v_mov_b32_e32 v118, v99
	s_waitcnt lgkmcnt(0)
	v_mov_b32_e32 v169, v108
	v_cndmask_b32_e32 v119, v181, v119, vcc
	v_lshlrev_b32_e32 v119, 2, v119
	ds_bpermute_b32 v164, v119, v102
	ds_bpermute_b32 v165, v119, v103
	ds_bpermute_b32 v99, v119, v99
	ds_bpermute_b32 v126, v119, v100
	ds_bpermute_b32 v127, v119, v101
	ds_bpermute_b32 v166, v119, v96
	ds_bpermute_b32 v167, v119, v97
	ds_bpermute_b32 v168, v119, v98
	s_waitcnt lgkmcnt(6)
	v_pk_mul_f32 v[164:165], v[140:141], v[164:165]
	s_waitcnt lgkmcnt(5)
	v_mul_f32_e32 v119, v140, v99
	v_mov_b32_e32 v108, v107
	v_mov_b32_e32 v107, v116
	v_mov_b32_e32 v116, v115
	s_waitcnt lgkmcnt(3)
	v_pk_mul_f32 v[126:127], v[140:141], v[126:127]
	s_waitcnt lgkmcnt(1)
	v_pk_mul_f32 v[166:167], v[140:141], v[166:167]
	s_waitcnt lgkmcnt(0)
	v_mul_f32_e32 v170, v140, v168
	v_mov_b32_e32 v168, v106
	v_mov_b32_e32 v106, v114
	v_pk_mul_f32 v[114:115], v[164:165], v[116:117]
	v_mov_b32_e32 v117, v124
	v_mov_b32_e32 v124, v123
	v_pk_mul_f32 v[112:113], v[118:119], v[112:113]
	v_pk_mul_f32 v[108:109], v[126:127], v[108:109]
	v_mov_b32_e32 v116, v122
	v_mul_f32_e32 v98, v98, v110
	v_mul_f32_e32 v110, v170, v111
	v_pk_mul_f32 v[118:119], v[166:167], v[124:125]
	v_mov_b32_e32 v99, v112
	v_mov_b32_e32 v111, v113
	v_pk_fma_f32 v[100:101], v[100:101], v[168:169], v[108:109]
	v_pk_fma_f32 v[102:103], v[102:103], v[106:107], v[114:115]
	v_pk_fma_f32 v[96:97], v[96:97], v[116:117], v[118:119]
	v_pk_add_f32 v[98:99], v[98:99], v[110:111]
	v_pk_mul_f32 v[108:109], s[22:23], v[102:103] op_sel_hi:[0,1]
	v_pk_mul_f32 v[106:107], s[22:23], v[100:101] op_sel_hi:[0,1]
	v_pk_mul_f32 v[114:115], s[22:23], v[98:99] op_sel_hi:[0,1]
	v_pk_mul_f32 v[110:111], s[22:23], v[96:97] op_sel_hi:[0,1]
	s_branch .LBB0_198

.LBB0_200:
	v_mov_b32_e32 v96, s15
	v_cndmask_b32_e64 v96, v177, v96, s[4:5]
	v_lshlrev_b32_e32 v96, 4, v96
	v_ashrrev_i32_e32 v97, 31, v96
	s_andn2_b64 vcc, exec, s[28:29]
	v_lshl_add_u32 v96, v96, 3, v249
	s_cbranch_vccnz .LBB0_204
	s_cmp_eq_u32 s13, 1
	s_cbranch_scc0 .LBB0_203
	ds_read_b128 v[98:101], v96
	ds_read_b128 v[102:105], v96 offset:16
	ds_read_b128 v[106:109], v96 offset:32
	ds_read_b128 v[110:113], v96 offset:48
	v_and_b32_e32 v116, 64, v181
	v_xor_b32_e32 v115, 32, v181
	v_add_u32_e32 v116, 64, v116
	v_cmp_lt_i32_e32 vcc, v115, v116
	v_mov_b32_e32 v114, v91
	s_waitcnt lgkmcnt(0)
	v_mov_b32_e32 v125, v100
	v_cndmask_b32_e32 v115, v181, v115, vcc
	v_lshlrev_b32_e32 v115, 2, v115
	ds_bpermute_b32 v118, v115, v94
	ds_bpermute_b32 v119, v115, v95
	ds_bpermute_b32 v124, v115, v90
	ds_bpermute_b32 v91, v115, v91
	ds_bpermute_b32 v116, v115, v92
	ds_bpermute_b32 v117, v115, v93
	ds_bpermute_b32 v122, v115, v88
	ds_bpermute_b32 v123, v115, v89
	s_waitcnt lgkmcnt(6)
	v_pk_mul_f32 v[118:119], v[140:141], v[118:119]
	s_waitcnt lgkmcnt(5)
	v_mul_f32_e32 v126, v140, v124
	s_waitcnt lgkmcnt(4)
	v_mul_f32_e32 v115, v140, v91
	v_mov_b32_e32 v100, v99
	v_mov_b32_e32 v99, v104
	v_mov_b32_e32 v104, v103
	s_waitcnt lgkmcnt(2)
	v_pk_mul_f32 v[116:117], v[140:141], v[116:117]
	s_waitcnt lgkmcnt(0)
	v_pk_mul_f32 v[122:123], v[140:141], v[122:123]
	v_mov_b32_e32 v124, v98
	v_mov_b32_e32 v98, v102
	v_pk_mul_f32 v[102:103], v[118:119], v[104:105]
	v_mov_b32_e32 v104, v106
	v_mov_b32_e32 v105, v108
	v_mov_b32_e32 v108, v107
	v_mul_f32_e32 v90, v90, v110
	v_mul_f32_e32 v106, v126, v111
	v_pk_mul_f32 v[110:111], v[114:115], v[112:113]
	v_pk_mul_f32 v[100:101], v[116:117], v[100:101]
	v_pk_mul_f32 v[108:109], v[122:123], v[108:109]
	v_mov_b32_e32 v91, v110
	v_mov_b32_e32 v107, v111
	v_pk_fma_f32 v[92:93], v[92:93], v[124:125], v[100:101]
	v_pk_fma_f32 v[94:95], v[94:95], v[98:99], v[102:103]
	v_pk_fma_f32 v[88:89], v[88:89], v[104:105], v[108:109]
	v_pk_add_f32 v[90:91], v[90:91], v[106:107]
	v_pk_mul_f32 v[100:101], s[22:23], v[94:95] op_sel_hi:[0,1]
	v_pk_mul_f32 v[98:99], s[22:23], v[92:93] op_sel_hi:[0,1]
	v_pk_mul_f32 v[104:105], s[22:23], v[90:91] op_sel_hi:[0,1]
	v_pk_mul_f32 v[102:103], s[22:23], v[88:89] op_sel_hi:[0,1]
	s_branch .LBB0_204

.LBB0_206:
	s_andn2_b64 vcc, exec, s[28:29]
	s_cbranch_vccnz .LBB0_210
	s_cmp_eq_u32 s13, 1
	s_cbranch_scc0 .LBB0_209
	ds_read_b128 v[90:93], v96
	ds_read_b128 v[98:101], v96 offset:16
	ds_read_b128 v[102:105], v96 offset:32
	s_nop 0
	ds_read_b128 v[94:97], v96 offset:48
	v_and_b32_e32 v108, 64, v181
	v_xor_b32_e32 v107, 32, v181
	v_add_u32_e32 v108, 64, v108
	v_cmp_lt_i32_e32 vcc, v107, v108
	v_mov_b32_e32 v106, v83
	s_waitcnt lgkmcnt(0)
	v_mov_b32_e32 v115, v92
	v_cndmask_b32_e32 v107, v181, v107, vcc
	v_lshlrev_b32_e32 v107, 2, v107
	ds_bpermute_b32 v110, v107, v86
	ds_bpermute_b32 v111, v107, v87
	ds_bpermute_b32 v83, v107, v83
	ds_bpermute_b32 v108, v107, v84
	ds_bpermute_b32 v109, v107, v85
	ds_bpermute_b32 v112, v107, v80
	ds_bpermute_b32 v113, v107, v81
	ds_bpermute_b32 v114, v107, v82
	s_waitcnt lgkmcnt(6)
	v_pk_mul_f32 v[110:111], v[140:141], v[110:111]
	s_waitcnt lgkmcnt(5)
	v_mul_f32_e32 v107, v140, v83
	v_mov_b32_e32 v92, v91
	v_mov_b32_e32 v91, v100
	v_mov_b32_e32 v100, v99
	s_waitcnt lgkmcnt(3)
	v_pk_mul_f32 v[108:109], v[140:141], v[108:109]
	s_waitcnt lgkmcnt(1)
	v_pk_mul_f32 v[112:113], v[140:141], v[112:113]
	s_waitcnt lgkmcnt(0)
	v_mul_f32_e32 v116, v140, v114
	v_mov_b32_e32 v114, v90
	v_mov_b32_e32 v90, v98
	v_pk_mul_f32 v[98:99], v[110:111], v[100:101]
	v_mov_b32_e32 v101, v104
	v_mov_b32_e32 v104, v103
	v_pk_mul_f32 v[96:97], v[106:107], v[96:97]
	v_pk_mul_f32 v[92:93], v[108:109], v[92:93]
	v_mov_b32_e32 v100, v102
	v_mul_f32_e32 v82, v82, v94
	v_mul_f32_e32 v94, v116, v95
	v_pk_mul_f32 v[102:103], v[112:113], v[104:105]
	v_mov_b32_e32 v83, v96
	v_mov_b32_e32 v95, v97
	v_pk_fma_f32 v[84:85], v[84:85], v[114:115], v[92:93]
	v_pk_fma_f32 v[86:87], v[86:87], v[90:91], v[98:99]
	v_pk_fma_f32 v[80:81], v[80:81], v[100:101], v[102:103]
	v_pk_add_f32 v[82:83], v[82:83], v[94:95]
	v_pk_mul_f32 v[92:93], s[22:23], v[86:87] op_sel_hi:[0,1]
	v_pk_mul_f32 v[90:91], s[22:23], v[84:85] op_sel_hi:[0,1]
	v_pk_mul_f32 v[98:99], s[22:23], v[82:83] op_sel_hi:[0,1]
	v_pk_mul_f32 v[94:95], s[22:23], v[80:81] op_sel_hi:[0,1]
	s_branch .LBB0_210

.LBB0_212:
	v_mov_b32_e32 v80, s15
	v_cndmask_b32_e64 v80, v179, v80, s[4:5]
	v_lshlrev_b32_e32 v80, 4, v80
	v_ashrrev_i32_e32 v81, 31, v80
	s_andn2_b64 vcc, exec, s[28:29]
	v_lshl_add_u32 v80, v80, 3, v249
	s_cbranch_vccnz .LBB0_216
	s_cmp_eq_u32 s13, 1
	s_cbranch_scc0 .LBB0_215
	ds_read_b128 v[82:85], v80
	ds_read_b128 v[86:89], v80 offset:16
	ds_read_b128 v[90:93], v80 offset:32
	ds_read_b128 v[94:97], v80 offset:48
	v_and_b32_e32 v100, 64, v181
	v_xor_b32_e32 v99, 32, v181
	v_add_u32_e32 v100, 64, v100
	v_cmp_lt_i32_e32 vcc, v99, v100
	v_mov_b32_e32 v98, v75
	s_waitcnt lgkmcnt(0)
	v_mov_b32_e32 v107, v84
	v_cndmask_b32_e32 v99, v181, v99, vcc
	v_lshlrev_b32_e32 v99, 2, v99
	ds_bpermute_b32 v102, v99, v78
	ds_bpermute_b32 v103, v99, v79
	ds_bpermute_b32 v106, v99, v74
	ds_bpermute_b32 v75, v99, v75
	ds_bpermute_b32 v100, v99, v76
	ds_bpermute_b32 v101, v99, v77
	ds_bpermute_b32 v104, v99, v72
	ds_bpermute_b32 v105, v99, v73
	s_waitcnt lgkmcnt(6)
	v_pk_mul_f32 v[102:103], v[140:141], v[102:103]
	s_waitcnt lgkmcnt(5)
	v_mul_f32_e32 v108, v140, v106
	s_waitcnt lgkmcnt(4)
	v_mul_f32_e32 v99, v140, v75
	v_mov_b32_e32 v84, v83
	v_mov_b32_e32 v83, v88
	v_mov_b32_e32 v88, v87
	s_waitcnt lgkmcnt(2)
	v_pk_mul_f32 v[100:101], v[140:141], v[100:101]
	s_waitcnt lgkmcnt(0)
	v_pk_mul_f32 v[104:105], v[140:141], v[104:105]
	v_mov_b32_e32 v106, v82
	v_mov_b32_e32 v82, v86
	v_pk_mul_f32 v[86:87], v[102:103], v[88:89]
	v_mov_b32_e32 v88, v90
	v_mov_b32_e32 v89, v92
	v_mov_b32_e32 v92, v91
	v_mul_f32_e32 v74, v74, v94
	v_mul_f32_e32 v90, v108, v95
	v_pk_mul_f32 v[94:95], v[98:99], v[96:97]
	v_pk_mul_f32 v[84:85], v[100:101], v[84:85]
	v_pk_mul_f32 v[92:93], v[104:105], v[92:93]
	v_mov_b32_e32 v75, v94
	v_mov_b32_e32 v91, v95
	v_pk_fma_f32 v[76:77], v[76:77], v[106:107], v[84:85]
	v_pk_fma_f32 v[78:79], v[78:79], v[82:83], v[86:87]
	v_pk_fma_f32 v[72:73], v[72:73], v[88:89], v[92:93]
	v_pk_add_f32 v[74:75], v[74:75], v[90:91]
	v_pk_mul_f32 v[84:85], s[22:23], v[78:79] op_sel_hi:[0,1]
	v_pk_mul_f32 v[82:83], s[22:23], v[76:77] op_sel_hi:[0,1]
	v_pk_mul_f32 v[88:89], s[22:23], v[74:75] op_sel_hi:[0,1]
	v_pk_mul_f32 v[86:87], s[22:23], v[72:73] op_sel_hi:[0,1]
	s_branch .LBB0_216

.LBB0_218:
	s_andn2_b64 vcc, exec, s[28:29]
	s_cbranch_vccnz .LBB0_222
	s_cmp_eq_u32 s13, 1
	s_cbranch_scc0 .LBB0_221
	ds_read_b128 v[74:77], v80
	ds_read_b128 v[82:85], v80 offset:16
	ds_read_b128 v[86:89], v80 offset:32
	s_nop 0
	ds_read_b128 v[78:81], v80 offset:48
	v_and_b32_e32 v92, 64, v181
	v_xor_b32_e32 v91, 32, v181
	v_add_u32_e32 v92, 64, v92
	v_cmp_lt_i32_e32 vcc, v91, v92
	v_mov_b32_e32 v90, v67
	s_waitcnt lgkmcnt(0)
	v_mov_b32_e32 v99, v76
	v_cndmask_b32_e32 v91, v181, v91, vcc
	v_lshlrev_b32_e32 v91, 2, v91
	ds_bpermute_b32 v94, v91, v70
	ds_bpermute_b32 v95, v91, v71
	ds_bpermute_b32 v67, v91, v67
	ds_bpermute_b32 v92, v91, v68
	ds_bpermute_b32 v93, v91, v69
	ds_bpermute_b32 v96, v91, v64
	ds_bpermute_b32 v97, v91, v65
	ds_bpermute_b32 v98, v91, v66
	s_waitcnt lgkmcnt(6)
	v_pk_mul_f32 v[94:95], v[140:141], v[94:95]
	s_waitcnt lgkmcnt(5)
	v_mul_f32_e32 v91, v140, v67
	v_mov_b32_e32 v76, v75
	v_mov_b32_e32 v75, v84
	v_mov_b32_e32 v84, v83
	s_waitcnt lgkmcnt(3)
	v_pk_mul_f32 v[92:93], v[140:141], v[92:93]
	s_waitcnt lgkmcnt(1)
	v_pk_mul_f32 v[96:97], v[140:141], v[96:97]
	s_waitcnt lgkmcnt(0)
	v_mul_f32_e32 v100, v140, v98
	v_mov_b32_e32 v98, v74
	v_mov_b32_e32 v74, v82
	v_pk_mul_f32 v[82:83], v[94:95], v[84:85]
	v_mov_b32_e32 v85, v88
	v_mov_b32_e32 v88, v87
	v_pk_mul_f32 v[80:81], v[90:91], v[80:81]
	v_pk_mul_f32 v[76:77], v[92:93], v[76:77]
	v_mov_b32_e32 v84, v86
	v_mul_f32_e32 v66, v66, v78
	v_mul_f32_e32 v78, v100, v79
	v_pk_mul_f32 v[86:87], v[96:97], v[88:89]
	v_mov_b32_e32 v67, v80
	v_mov_b32_e32 v79, v81
	v_pk_fma_f32 v[68:69], v[68:69], v[98:99], v[76:77]
	v_pk_fma_f32 v[70:71], v[70:71], v[74:75], v[82:83]
	v_pk_fma_f32 v[64:65], v[64:65], v[84:85], v[86:87]
	v_pk_add_f32 v[66:67], v[66:67], v[78:79]
	v_pk_mul_f32 v[76:77], s[22:23], v[70:71] op_sel_hi:[0,1]
	v_pk_mul_f32 v[74:75], s[22:23], v[68:69] op_sel_hi:[0,1]
	v_pk_mul_f32 v[82:83], s[22:23], v[66:67] op_sel_hi:[0,1]
	v_pk_mul_f32 v[78:79], s[22:23], v[64:65] op_sel_hi:[0,1]
	s_branch .LBB0_222

.LBB0_224:
	s_add_i32 s15, s15, 2
	v_mov_b32_e32 v64, s15
	v_cndmask_b32_e64 v64, v174, v64, s[4:5]
	v_lshlrev_b32_e32 v64, 4, v64
	v_ashrrev_i32_e32 v65, 31, v64
	s_andn2_b64 vcc, exec, s[28:29]
	v_lshl_add_u32 v64, v64, 3, v249
	s_cbranch_vccnz .LBB0_228
	s_cmp_eq_u32 s13, 1
	s_cbranch_scc0 .LBB0_227
	ds_read_b128 v[66:69], v64
	ds_read_b128 v[70:73], v64 offset:16
	ds_read_b128 v[74:77], v64 offset:32
	ds_read_b128 v[78:81], v64 offset:48
	v_and_b32_e32 v84, 64, v181
	v_xor_b32_e32 v83, 32, v181
	v_add_u32_e32 v84, 64, v84
	v_cmp_lt_i32_e32 vcc, v83, v84
	v_mov_b32_e32 v82, v59
	s_waitcnt lgkmcnt(0)
	v_mov_b32_e32 v91, v68
	v_cndmask_b32_e32 v83, v181, v83, vcc
	v_lshlrev_b32_e32 v83, 2, v83
	ds_bpermute_b32 v86, v83, v62
	ds_bpermute_b32 v87, v83, v63
	ds_bpermute_b32 v90, v83, v58
	ds_bpermute_b32 v59, v83, v59
	ds_bpermute_b32 v84, v83, v60
	ds_bpermute_b32 v85, v83, v61
	ds_bpermute_b32 v88, v83, v56
	ds_bpermute_b32 v89, v83, v57
	s_waitcnt lgkmcnt(6)
	v_pk_mul_f32 v[86:87], v[140:141], v[86:87]
	s_waitcnt lgkmcnt(5)
	v_mul_f32_e32 v92, v140, v90
	s_waitcnt lgkmcnt(4)
	v_mul_f32_e32 v83, v140, v59
	v_mov_b32_e32 v68, v67
	v_mov_b32_e32 v67, v72
	v_mov_b32_e32 v72, v71
	s_waitcnt lgkmcnt(2)
	v_pk_mul_f32 v[84:85], v[140:141], v[84:85]
	s_waitcnt lgkmcnt(0)
	v_pk_mul_f32 v[88:89], v[140:141], v[88:89]
	v_mov_b32_e32 v90, v66
	v_mov_b32_e32 v66, v70
	v_pk_mul_f32 v[70:71], v[86:87], v[72:73]
	v_mov_b32_e32 v72, v74
	v_mov_b32_e32 v73, v76
	v_mov_b32_e32 v76, v75
	v_mul_f32_e32 v58, v58, v78
	v_mul_f32_e32 v74, v92, v79
	v_pk_mul_f32 v[78:79], v[82:83], v[80:81]
	v_pk_mul_f32 v[68:69], v[84:85], v[68:69]
	v_pk_mul_f32 v[76:77], v[88:89], v[76:77]
	v_mov_b32_e32 v59, v78
	v_mov_b32_e32 v75, v79
	v_pk_fma_f32 v[60:61], v[60:61], v[90:91], v[68:69]
	v_pk_fma_f32 v[62:63], v[62:63], v[66:67], v[70:71]
	v_pk_fma_f32 v[56:57], v[56:57], v[72:73], v[76:77]
	v_pk_add_f32 v[58:59], v[58:59], v[74:75]
	v_pk_mul_f32 v[68:69], s[22:23], v[62:63] op_sel_hi:[0,1]
	v_pk_mul_f32 v[66:67], s[22:23], v[60:61] op_sel_hi:[0,1]
	v_pk_mul_f32 v[72:73], s[22:23], v[58:59] op_sel_hi:[0,1]
	v_pk_mul_f32 v[70:71], s[22:23], v[56:57] op_sel_hi:[0,1]
	s_branch .LBB0_228

.LBB0_230:
	s_andn2_b64 vcc, exec, s[28:29]
	s_cbranch_vccnz .LBB0_234
	s_cmp_eq_u32 s13, 1
	s_cbranch_scc0 .LBB0_233
	ds_read_b128 v[58:61], v64
	ds_read_b128 v[66:69], v64 offset:16
	ds_read_b128 v[70:73], v64 offset:32
	s_nop 0
	ds_read_b128 v[62:65], v64 offset:48
	v_and_b32_e32 v76, 64, v181
	v_xor_b32_e32 v75, 32, v181
	v_add_u32_e32 v76, 64, v76
	v_cmp_lt_i32_e32 vcc, v75, v76
	v_mov_b32_e32 v74, v51
	s_waitcnt lgkmcnt(0)
	v_mov_b32_e32 v83, v60
	v_cndmask_b32_e32 v75, v181, v75, vcc
	v_lshlrev_b32_e32 v75, 2, v75
	ds_bpermute_b32 v78, v75, v54
	ds_bpermute_b32 v79, v75, v55
	ds_bpermute_b32 v51, v75, v51
	ds_bpermute_b32 v76, v75, v52
	ds_bpermute_b32 v77, v75, v53
	ds_bpermute_b32 v80, v75, v48
	ds_bpermute_b32 v81, v75, v49
	ds_bpermute_b32 v82, v75, v50
	s_waitcnt lgkmcnt(6)
	v_pk_mul_f32 v[78:79], v[140:141], v[78:79]
	s_waitcnt lgkmcnt(5)
	v_mul_f32_e32 v75, v140, v51
	v_mov_b32_e32 v60, v59
	v_mov_b32_e32 v59, v68
	v_mov_b32_e32 v68, v67
	s_waitcnt lgkmcnt(3)
	v_pk_mul_f32 v[76:77], v[140:141], v[76:77]
	s_waitcnt lgkmcnt(1)
	v_pk_mul_f32 v[80:81], v[140:141], v[80:81]
	s_waitcnt lgkmcnt(0)
	v_mul_f32_e32 v84, v140, v82
	v_mov_b32_e32 v82, v58
	v_mov_b32_e32 v58, v66
	v_pk_mul_f32 v[66:67], v[78:79], v[68:69]
	v_mov_b32_e32 v69, v72
	v_mov_b32_e32 v72, v71
	v_pk_mul_f32 v[64:65], v[74:75], v[64:65]
	v_pk_mul_f32 v[60:61], v[76:77], v[60:61]
	v_mov_b32_e32 v68, v70
	v_mul_f32_e32 v50, v50, v62
	v_mul_f32_e32 v62, v84, v63
	v_pk_mul_f32 v[70:71], v[80:81], v[72:73]
	v_mov_b32_e32 v51, v64
	v_mov_b32_e32 v63, v65
	v_pk_fma_f32 v[52:53], v[52:53], v[82:83], v[60:61]
	v_pk_fma_f32 v[54:55], v[54:55], v[58:59], v[66:67]
	v_pk_fma_f32 v[48:49], v[48:49], v[68:69], v[70:71]
	v_pk_add_f32 v[50:51], v[50:51], v[62:63]
	v_pk_mul_f32 v[60:61], s[22:23], v[54:55] op_sel_hi:[0,1]
	v_pk_mul_f32 v[58:59], s[22:23], v[52:53] op_sel_hi:[0,1]
	v_pk_mul_f32 v[66:67], s[22:23], v[50:51] op_sel_hi:[0,1]
	v_pk_mul_f32 v[62:63], s[22:23], v[48:49] op_sel_hi:[0,1]
	s_branch .LBB0_234

.LBB0_236:
	v_mov_b32_e32 v48, s15
	v_cndmask_b32_e64 v48, v176, v48, s[4:5]
	v_lshlrev_b32_e32 v48, 4, v48
	v_ashrrev_i32_e32 v49, 31, v48
	s_andn2_b64 vcc, exec, s[28:29]
	v_lshl_add_u32 v48, v48, 3, v249
	s_cbranch_vccnz .LBB0_240
	s_cmp_eq_u32 s13, 1
	s_cbranch_scc0 .LBB0_239
	ds_read_b128 v[50:53], v48
	ds_read_b128 v[54:57], v48 offset:16
	ds_read_b128 v[58:61], v48 offset:32
	ds_read_b128 v[62:65], v48 offset:48
	v_and_b32_e32 v68, 64, v181
	v_xor_b32_e32 v67, 32, v181
	v_add_u32_e32 v68, 64, v68
	v_cmp_lt_i32_e32 vcc, v67, v68
	v_mov_b32_e32 v66, v43
	s_waitcnt lgkmcnt(0)
	v_mov_b32_e32 v75, v52
	v_cndmask_b32_e32 v67, v181, v67, vcc
	v_lshlrev_b32_e32 v67, 2, v67
	ds_bpermute_b32 v70, v67, v46
	ds_bpermute_b32 v71, v67, v47
	ds_bpermute_b32 v74, v67, v42
	ds_bpermute_b32 v43, v67, v43
	ds_bpermute_b32 v68, v67, v44
	ds_bpermute_b32 v69, v67, v45
	ds_bpermute_b32 v72, v67, v40
	ds_bpermute_b32 v73, v67, v41
	s_waitcnt lgkmcnt(6)
	v_pk_mul_f32 v[70:71], v[140:141], v[70:71]
	s_waitcnt lgkmcnt(5)
	v_mul_f32_e32 v76, v140, v74
	s_waitcnt lgkmcnt(4)
	v_mul_f32_e32 v67, v140, v43
	v_mov_b32_e32 v52, v51
	v_mov_b32_e32 v51, v56
	v_mov_b32_e32 v56, v55
	s_waitcnt lgkmcnt(2)
	v_pk_mul_f32 v[68:69], v[140:141], v[68:69]
	s_waitcnt lgkmcnt(0)
	v_pk_mul_f32 v[72:73], v[140:141], v[72:73]
	v_mov_b32_e32 v74, v50
	v_mov_b32_e32 v50, v54
	v_pk_mul_f32 v[54:55], v[70:71], v[56:57]
	v_mov_b32_e32 v56, v58
	v_mov_b32_e32 v57, v60
	v_mov_b32_e32 v60, v59
	v_mul_f32_e32 v42, v42, v62
	v_mul_f32_e32 v58, v76, v63
	v_pk_mul_f32 v[62:63], v[66:67], v[64:65]
	v_pk_mul_f32 v[52:53], v[68:69], v[52:53]
	v_pk_mul_f32 v[60:61], v[72:73], v[60:61]
	v_mov_b32_e32 v43, v62
	v_mov_b32_e32 v59, v63
	v_pk_fma_f32 v[44:45], v[44:45], v[74:75], v[52:53]
	v_pk_fma_f32 v[46:47], v[46:47], v[50:51], v[54:55]
	v_pk_fma_f32 v[40:41], v[40:41], v[56:57], v[60:61]
	v_pk_add_f32 v[42:43], v[42:43], v[58:59]
	v_pk_mul_f32 v[52:53], s[22:23], v[46:47] op_sel_hi:[0,1]
	v_pk_mul_f32 v[50:51], s[22:23], v[44:45] op_sel_hi:[0,1]
	v_pk_mul_f32 v[56:57], s[22:23], v[42:43] op_sel_hi:[0,1]
	v_pk_mul_f32 v[54:55], s[22:23], v[40:41] op_sel_hi:[0,1]
	s_branch .LBB0_240

.LBB0_242:
	s_andn2_b64 vcc, exec, s[28:29]
	s_cbranch_vccnz .LBB0_246
	s_cmp_eq_u32 s13, 1
	s_cbranch_scc0 .LBB0_245
	ds_read_b128 v[42:45], v48
	ds_read_b128 v[50:53], v48 offset:16
	ds_read_b128 v[54:57], v48 offset:32
	s_nop 0
	ds_read_b128 v[46:49], v48 offset:48
	v_and_b32_e32 v60, 64, v181
	v_xor_b32_e32 v59, 32, v181
	v_add_u32_e32 v60, 64, v60
	v_cmp_lt_i32_e32 vcc, v59, v60
	v_mov_b32_e32 v58, v35
	s_waitcnt lgkmcnt(0)
	v_mov_b32_e32 v67, v44
	v_cndmask_b32_e32 v59, v181, v59, vcc
	v_lshlrev_b32_e32 v59, 2, v59
	ds_bpermute_b32 v62, v59, v38
	ds_bpermute_b32 v63, v59, v39
	ds_bpermute_b32 v35, v59, v35
	ds_bpermute_b32 v60, v59, v36
	ds_bpermute_b32 v61, v59, v37
	ds_bpermute_b32 v64, v59, v32
	ds_bpermute_b32 v65, v59, v33
	ds_bpermute_b32 v66, v59, v34
	s_waitcnt lgkmcnt(6)
	v_pk_mul_f32 v[62:63], v[140:141], v[62:63]
	s_waitcnt lgkmcnt(5)
	v_mul_f32_e32 v59, v140, v35
	v_mov_b32_e32 v44, v43
	v_mov_b32_e32 v43, v52
	v_mov_b32_e32 v52, v51
	s_waitcnt lgkmcnt(3)
	v_pk_mul_f32 v[60:61], v[140:141], v[60:61]
	s_waitcnt lgkmcnt(1)
	v_pk_mul_f32 v[64:65], v[140:141], v[64:65]
	s_waitcnt lgkmcnt(0)
	v_mul_f32_e32 v68, v140, v66
	v_mov_b32_e32 v66, v42
	v_mov_b32_e32 v42, v50
	v_pk_mul_f32 v[50:51], v[62:63], v[52:53]
	v_mov_b32_e32 v53, v56
	v_mov_b32_e32 v56, v55
	v_pk_mul_f32 v[48:49], v[58:59], v[48:49]
	v_pk_mul_f32 v[44:45], v[60:61], v[44:45]
	v_mov_b32_e32 v52, v54
	v_mul_f32_e32 v34, v34, v46
	v_mul_f32_e32 v46, v68, v47
	v_pk_mul_f32 v[54:55], v[64:65], v[56:57]
	v_mov_b32_e32 v35, v48
	v_mov_b32_e32 v47, v49
	v_pk_fma_f32 v[36:37], v[36:37], v[66:67], v[44:45]
	v_pk_fma_f32 v[38:39], v[38:39], v[42:43], v[50:51]
	v_pk_fma_f32 v[32:33], v[32:33], v[52:53], v[54:55]
	v_pk_add_f32 v[34:35], v[34:35], v[46:47]
	v_pk_mul_f32 v[44:45], s[22:23], v[38:39] op_sel_hi:[0,1]
	v_pk_mul_f32 v[42:43], s[22:23], v[36:37] op_sel_hi:[0,1]
	v_pk_mul_f32 v[50:51], s[22:23], v[34:35] op_sel_hi:[0,1]
	v_pk_mul_f32 v[46:47], s[22:23], v[32:33] op_sel_hi:[0,1]
	s_branch .LBB0_246

.LBB0_248:
	v_mov_b32_e32 v32, s15
	v_cndmask_b32_e64 v32, v177, v32, s[4:5]
	v_lshlrev_b32_e32 v32, 4, v32
	v_ashrrev_i32_e32 v33, 31, v32
	s_andn2_b64 vcc, exec, s[28:29]
	v_lshl_add_u32 v32, v32, 3, v249
	s_cbranch_vccnz .LBB0_252
	s_cmp_eq_u32 s13, 1
	s_cbranch_scc0 .LBB0_251
	ds_read_b128 v[34:37], v32
	ds_read_b128 v[38:41], v32 offset:16
	ds_read_b128 v[42:45], v32 offset:32
	ds_read_b128 v[46:49], v32 offset:48
	v_and_b32_e32 v52, 64, v181
	v_xor_b32_e32 v51, 32, v181
	v_add_u32_e32 v52, 64, v52
	v_cmp_lt_i32_e32 vcc, v51, v52
	v_mov_b32_e32 v50, v27
	s_waitcnt lgkmcnt(0)
	v_mov_b32_e32 v59, v36
	v_cndmask_b32_e32 v51, v181, v51, vcc
	v_lshlrev_b32_e32 v51, 2, v51
	ds_bpermute_b32 v54, v51, v30
	ds_bpermute_b32 v55, v51, v31
	ds_bpermute_b32 v58, v51, v26
	ds_bpermute_b32 v27, v51, v27
	ds_bpermute_b32 v52, v51, v28
	ds_bpermute_b32 v53, v51, v29
	ds_bpermute_b32 v56, v51, v24
	ds_bpermute_b32 v57, v51, v25
	s_waitcnt lgkmcnt(6)
	v_pk_mul_f32 v[54:55], v[140:141], v[54:55]
	s_waitcnt lgkmcnt(5)
	v_mul_f32_e32 v60, v140, v58
	s_waitcnt lgkmcnt(4)
	v_mul_f32_e32 v51, v140, v27
	v_mov_b32_e32 v36, v35
	v_mov_b32_e32 v35, v40
	v_mov_b32_e32 v40, v39
	s_waitcnt lgkmcnt(2)
	v_pk_mul_f32 v[52:53], v[140:141], v[52:53]
	s_waitcnt lgkmcnt(0)
	v_pk_mul_f32 v[56:57], v[140:141], v[56:57]
	v_mov_b32_e32 v58, v34
	v_mov_b32_e32 v34, v38
	v_pk_mul_f32 v[38:39], v[54:55], v[40:41]
	v_mov_b32_e32 v40, v42
	v_mov_b32_e32 v41, v44
	v_mov_b32_e32 v44, v43
	v_mul_f32_e32 v26, v26, v46
	v_mul_f32_e32 v42, v60, v47
	v_pk_mul_f32 v[46:47], v[50:51], v[48:49]
	v_pk_mul_f32 v[36:37], v[52:53], v[36:37]
	v_pk_mul_f32 v[44:45], v[56:57], v[44:45]
	v_mov_b32_e32 v27, v46
	v_mov_b32_e32 v43, v47
	v_pk_fma_f32 v[28:29], v[28:29], v[58:59], v[36:37]
	v_pk_fma_f32 v[30:31], v[30:31], v[34:35], v[38:39]
	v_pk_fma_f32 v[24:25], v[24:25], v[40:41], v[44:45]
	v_pk_add_f32 v[26:27], v[26:27], v[42:43]
	v_pk_mul_f32 v[36:37], s[22:23], v[30:31] op_sel_hi:[0,1]
	v_pk_mul_f32 v[34:35], s[22:23], v[28:29] op_sel_hi:[0,1]
	v_pk_mul_f32 v[40:41], s[22:23], v[26:27] op_sel_hi:[0,1]
	v_pk_mul_f32 v[38:39], s[22:23], v[24:25] op_sel_hi:[0,1]
	s_branch .LBB0_252

.LBB0_254:
	s_andn2_b64 vcc, exec, s[28:29]
	s_cbranch_vccnz .LBB0_258
	s_cmp_eq_u32 s13, 1
	s_cbranch_scc0 .LBB0_257
	ds_read_b128 v[26:29], v32
	ds_read_b128 v[34:37], v32 offset:16
	ds_read_b128 v[38:41], v32 offset:32
	s_nop 0
	ds_read_b128 v[30:33], v32 offset:48
	v_and_b32_e32 v44, 64, v181
	v_xor_b32_e32 v43, 32, v181
	v_add_u32_e32 v44, 64, v44
	v_cmp_lt_i32_e32 vcc, v43, v44
	v_mov_b32_e32 v42, v19
	s_waitcnt lgkmcnt(0)
	v_mov_b32_e32 v51, v28
	v_cndmask_b32_e32 v43, v181, v43, vcc
	v_lshlrev_b32_e32 v43, 2, v43
	ds_bpermute_b32 v46, v43, v22
	ds_bpermute_b32 v47, v43, v23
	ds_bpermute_b32 v19, v43, v19
	ds_bpermute_b32 v44, v43, v20
	ds_bpermute_b32 v45, v43, v21
	ds_bpermute_b32 v48, v43, v16
	ds_bpermute_b32 v49, v43, v17
	ds_bpermute_b32 v50, v43, v18
	s_waitcnt lgkmcnt(6)
	v_pk_mul_f32 v[46:47], v[140:141], v[46:47]
	s_waitcnt lgkmcnt(5)
	v_mul_f32_e32 v43, v140, v19
	v_mov_b32_e32 v28, v27
	v_mov_b32_e32 v27, v36
	v_mov_b32_e32 v36, v35
	s_waitcnt lgkmcnt(3)
	v_pk_mul_f32 v[44:45], v[140:141], v[44:45]
	s_waitcnt lgkmcnt(1)
	v_pk_mul_f32 v[48:49], v[140:141], v[48:49]
	s_waitcnt lgkmcnt(0)
	v_mul_f32_e32 v52, v140, v50
	v_mov_b32_e32 v50, v26
	v_mov_b32_e32 v26, v34
	v_pk_mul_f32 v[34:35], v[46:47], v[36:37]
	v_mov_b32_e32 v37, v40
	v_mov_b32_e32 v40, v39
	v_pk_mul_f32 v[32:33], v[42:43], v[32:33]
	v_pk_mul_f32 v[28:29], v[44:45], v[28:29]
	v_mov_b32_e32 v36, v38
	v_mul_f32_e32 v18, v18, v30
	v_mul_f32_e32 v30, v52, v31
	v_pk_mul_f32 v[38:39], v[48:49], v[40:41]
	v_mov_b32_e32 v19, v32
	v_mov_b32_e32 v31, v33
	v_pk_fma_f32 v[20:21], v[20:21], v[50:51], v[28:29]
	v_pk_fma_f32 v[22:23], v[22:23], v[26:27], v[34:35]
	v_pk_fma_f32 v[16:17], v[16:17], v[36:37], v[38:39]
	v_pk_add_f32 v[18:19], v[18:19], v[30:31]
	v_pk_mul_f32 v[28:29], s[22:23], v[22:23] op_sel_hi:[0,1]
	v_pk_mul_f32 v[26:27], s[22:23], v[20:21] op_sel_hi:[0,1]
	v_pk_mul_f32 v[34:35], s[22:23], v[18:19] op_sel_hi:[0,1]
	v_pk_mul_f32 v[30:31], s[22:23], v[16:17] op_sel_hi:[0,1]
	s_branch .LBB0_258

.LBB0_260:
	v_mov_b32_e32 v16, s15
	v_cndmask_b32_e64 v16, v179, v16, s[4:5]
	v_lshlrev_b32_e32 v16, 4, v16
	v_ashrrev_i32_e32 v17, 31, v16
	s_andn2_b64 vcc, exec, s[28:29]
	v_lshl_add_u32 v16, v16, 3, v249
	s_cbranch_vccnz .LBB0_264
	s_cmp_eq_u32 s13, 1
	s_cbranch_scc0 .LBB0_263
	ds_read_b128 v[18:21], v16
	ds_read_b128 v[22:25], v16 offset:16
	ds_read_b128 v[26:29], v16 offset:32
	ds_read_b128 v[30:33], v16 offset:48
	v_and_b32_e32 v36, 64, v181
	v_xor_b32_e32 v35, 32, v181
	v_add_u32_e32 v36, 64, v36
	v_cmp_lt_i32_e32 vcc, v35, v36
	v_mov_b32_e32 v34, v11
	s_waitcnt lgkmcnt(0)
	v_mov_b32_e32 v43, v20
	v_cndmask_b32_e32 v35, v181, v35, vcc
	v_lshlrev_b32_e32 v35, 2, v35
	ds_bpermute_b32 v38, v35, v14
	ds_bpermute_b32 v39, v35, v15
	ds_bpermute_b32 v42, v35, v10
	ds_bpermute_b32 v11, v35, v11
	ds_bpermute_b32 v36, v35, v12
	ds_bpermute_b32 v37, v35, v13
	ds_bpermute_b32 v40, v35, v8
	ds_bpermute_b32 v41, v35, v9
	s_waitcnt lgkmcnt(6)
	v_pk_mul_f32 v[38:39], v[140:141], v[38:39]
	s_waitcnt lgkmcnt(5)
	v_mul_f32_e32 v44, v140, v42
	s_waitcnt lgkmcnt(4)
	v_mul_f32_e32 v35, v140, v11
	v_mov_b32_e32 v20, v19
	v_mov_b32_e32 v19, v24
	v_mov_b32_e32 v24, v23
	s_waitcnt lgkmcnt(2)
	v_pk_mul_f32 v[36:37], v[140:141], v[36:37]
	s_waitcnt lgkmcnt(0)
	v_pk_mul_f32 v[40:41], v[140:141], v[40:41]
	v_mov_b32_e32 v42, v18
	v_mov_b32_e32 v18, v22
	v_pk_mul_f32 v[22:23], v[38:39], v[24:25]
	v_mov_b32_e32 v24, v26
	v_mov_b32_e32 v25, v28
	v_mov_b32_e32 v28, v27
	v_mul_f32_e32 v10, v10, v30
	v_mul_f32_e32 v26, v44, v31
	v_pk_mul_f32 v[30:31], v[34:35], v[32:33]
	v_pk_mul_f32 v[20:21], v[36:37], v[20:21]
	v_pk_mul_f32 v[28:29], v[40:41], v[28:29]
	v_mov_b32_e32 v11, v30
	v_mov_b32_e32 v27, v31
	v_pk_fma_f32 v[12:13], v[12:13], v[42:43], v[20:21]
	v_pk_fma_f32 v[14:15], v[14:15], v[18:19], v[22:23]
	v_pk_fma_f32 v[8:9], v[8:9], v[24:25], v[28:29]
	v_pk_add_f32 v[10:11], v[10:11], v[26:27]
	v_pk_mul_f32 v[20:21], s[22:23], v[14:15] op_sel_hi:[0,1]
	v_pk_mul_f32 v[18:19], s[22:23], v[12:13] op_sel_hi:[0,1]
	v_pk_mul_f32 v[24:25], s[22:23], v[10:11] op_sel_hi:[0,1]
	v_pk_mul_f32 v[22:23], s[22:23], v[8:9] op_sel_hi:[0,1]
	s_branch .LBB0_264

.LBB0_266:
	s_andn2_b64 vcc, exec, s[24:25]
	s_cbranch_vccnz .LBB0_270
	s_cmp_eq_u32 s13, 1
	s_cbranch_scc0 .LBB0_269
	ds_read_b128 v[10:13], v16
	ds_read_b128 v[18:21], v16 offset:16
	ds_read_b128 v[22:25], v16 offset:32
	s_nop 0
	ds_read_b128 v[14:17], v16 offset:48
	v_and_b32_e32 v28, 64, v181
	v_xor_b32_e32 v27, 32, v181
	v_add_u32_e32 v28, 64, v28
	v_cmp_lt_i32_e32 vcc, v27, v28
	v_mov_b32_e32 v26, v3
	s_waitcnt lgkmcnt(0)
	v_mov_b32_e32 v35, v12
	v_cndmask_b32_e32 v27, v181, v27, vcc
	v_lshlrev_b32_e32 v27, 2, v27
	ds_bpermute_b32 v30, v27, v6
	ds_bpermute_b32 v31, v27, v7
	ds_bpermute_b32 v3, v27, v3
	ds_bpermute_b32 v28, v27, v4
	ds_bpermute_b32 v29, v27, v5
	ds_bpermute_b32 v32, v27, v0
	ds_bpermute_b32 v33, v27, v1
	ds_bpermute_b32 v34, v27, v2
	s_waitcnt lgkmcnt(6)
	v_pk_mul_f32 v[30:31], v[140:141], v[30:31]
	s_waitcnt lgkmcnt(5)
	v_mul_f32_e32 v27, v140, v3
	v_mov_b32_e32 v12, v11
	v_mov_b32_e32 v11, v20
	v_mov_b32_e32 v20, v19
	s_waitcnt lgkmcnt(3)
	v_pk_mul_f32 v[28:29], v[140:141], v[28:29]
	s_waitcnt lgkmcnt(1)
	v_pk_mul_f32 v[32:33], v[140:141], v[32:33]
	s_waitcnt lgkmcnt(0)
	v_mul_f32_e32 v36, v140, v34
	v_mov_b32_e32 v34, v10
	v_mov_b32_e32 v10, v18
	v_pk_mul_f32 v[18:19], v[30:31], v[20:21]
	v_mov_b32_e32 v21, v24
	v_mov_b32_e32 v24, v23
	v_pk_mul_f32 v[16:17], v[26:27], v[16:17]
	v_pk_mul_f32 v[12:13], v[28:29], v[12:13]
	v_mov_b32_e32 v20, v22
	v_mul_f32_e32 v2, v2, v14
	v_mul_f32_e32 v14, v36, v15
	v_pk_mul_f32 v[22:23], v[32:33], v[24:25]
	v_mov_b32_e32 v3, v16
	v_mov_b32_e32 v15, v17
	v_pk_fma_f32 v[4:5], v[4:5], v[34:35], v[12:13]
	v_pk_fma_f32 v[6:7], v[6:7], v[10:11], v[18:19]
	v_pk_fma_f32 v[0:1], v[0:1], v[20:21], v[22:23]
	v_pk_add_f32 v[2:3], v[2:3], v[14:15]
	v_pk_mul_f32 v[12:13], s[22:23], v[6:7] op_sel_hi:[0,1]
	v_pk_mul_f32 v[10:11], s[22:23], v[4:5] op_sel_hi:[0,1]
	v_pk_mul_f32 v[18:19], s[22:23], v[2:3] op_sel_hi:[0,1]
	v_pk_mul_f32 v[14:15], s[22:23], v[0:1] op_sel_hi:[0,1]
	s_branch .LBB0_270

	.amdhsa_kernel _Z10hybrid_fwd6Params
		.amdhsa_group_segment_fixed_size 0
		.amdhsa_private_segment_fixed_size 0
		.amdhsa_kernarg_size 464
		.amdhsa_user_sgpr_count 2
		.amdhsa_user_sgpr_dispatch_ptr 0
		.amdhsa_user_sgpr_queue_ptr 0
		.amdhsa_user_sgpr_kernarg_segment_ptr 1
		.amdhsa_user_sgpr_dispatch_id 0
		.amdhsa_user_sgpr_kernarg_preload_length 0
		.amdhsa_user_sgpr_kernarg_preload_offset 0
		.amdhsa_user_sgpr_private_segment_size 0
		.amdhsa_uses_dynamic_stack 0
		.amdhsa_enable_private_segment 0
		.amdhsa_system_sgpr_workgroup_id_x 1
		.amdhsa_system_sgpr_workgroup_id_y 0
		.amdhsa_system_sgpr_workgroup_id_z 0
		.amdhsa_system_sgpr_workgroup_info 0
		.amdhsa_system_vgpr_workitem_id 2
		.amdhsa_next_free_vgpr 256
		.amdhsa_next_free_sgpr 99
		.amdhsa_accum_offset 256
		.amdhsa_reserve_vcc 1
		.amdhsa_float_round_mode_32 0
		.amdhsa_float_round_mode_16_64 0
		.amdhsa_float_denorm_mode_32 3
		.amdhsa_float_denorm_mode_16_64 3
		.amdhsa_dx10_clamp 1
		.amdhsa_ieee_mode 1
		.amdhsa_fp16_overflow 0
		.amdhsa_tg_split 0
		.amdhsa_exception_fp_ieee_invalid_op 0
		.amdhsa_exception_fp_denorm_src 0
		.amdhsa_exception_fp_ieee_div_zero 0
		.amdhsa_exception_fp_ieee_overflow 0
		.amdhsa_exception_fp_ieee_underflow 0
		.amdhsa_exception_fp_ieee_inexact 0
		.amdhsa_exception_int_div_zero 0
	.end_amdhsa_kernel

amdhsa.kernels:
  - .agpr_count:     0
    .args:
      - .offset:         0
        .size:           208
        .value_kind:     by_value
      - .offset:         208
        .size:           4
        .value_kind:     hidden_block_count_x
      - .offset:         212
        .size:           4
        .value_kind:     hidden_block_count_y
      - .offset:         216
        .size:           4
        .value_kind:     hidden_block_count_z
      - .offset:         220
        .size:           2
        .value_kind:     hidden_group_size_x
      - .offset:         222
        .size:           2
        .value_kind:     hidden_group_size_y
      - .offset:         224
        .size:           2
        .value_kind:     hidden_group_size_z
      - .offset:         226
        .size:           2
        .value_kind:     hidden_remainder_x
      - .offset:         228
        .size:           2
        .value_kind:     hidden_remainder_y
      - .offset:         230
        .size:           2
        .value_kind:     hidden_remainder_z
      - .offset:         248
        .size:           8
        .value_kind:     hidden_global_offset_x
      - .offset:         256
        .size:           8
        .value_kind:     hidden_global_offset_y
      - .offset:         264
        .size:           8
        .value_kind:     hidden_global_offset_z
      - .offset:         272
        .size:           2
        .value_kind:     hidden_grid_dims
      - .offset:         296
        .size:           8
        .value_kind:     hidden_multigrid_sync_arg
      - .offset:         328
        .size:           4
        .value_kind:     hidden_dynamic_lds_size
    .group_segment_fixed_size: 0
    .kernarg_segment_align: 8
    .kernarg_segment_size: 464
    .language:       OpenCL C
    .language_version:
      - 2
      - 0
    .max_flat_workgroup_size: 512
    .name:           _Z10hybrid_fwd6Params
    .private_segment_fixed_size: 0
    .sgpr_count:     105
    .sgpr_spill_count: 0
    .symbol:         _Z10hybrid_fwd6Params.kd
    .uniform_work_group_size: 1
    .uses_dynamic_stack: false
    .vgpr_count:     256
    .vgpr_spill_count: 0
    .wavefront_size: 64
